# GEMM K-loop heads and MLA main loop head aligned to 64 bytes (s_nop padding)
# speedup vs baseline: 1.0080x; 1.0030x over previous
.LBB0_252:
	s_ashr_i32 s19, s18, 31
	s_lshl_b64 s[0:1], s[18:19], 19
	s_add_u32 s20, s33, s0
	s_addc_u32 s21, s34, s1
	s_and_b64 s[0:1], s[4:5], exec
	s_cselect_b32 s19, s21, s31
	s_cselect_b32 s50, s20, s30
	s_ashr_i32 s11, s10, 31
	s_lshl_b64 s[0:1], s[10:11], 19
	s_add_u32 s22, s35, s0
	s_addc_u32 s23, s36, s1
	s_and_b64 s[0:1], s[4:5], exec
	s_cselect_b32 s11, s23, s27
	s_cselect_b32 s51, s22, s26
	s_add_u32 s0, s30, 0x40080
	s_addc_u32 s1, s31, 0
	s_add_u32 s52, s26, 0x100
	v_mov_b32_e32 v0, 0
	s_addc_u32 s53, s27, 0
	s_mov_b32 s54, -2
	v_mov_b32_e32 v1, v0
	v_mov_b32_e32 v2, v0
	v_mov_b32_e32 v3, v0
	v_mov_b32_e32 v8, v0
	v_mov_b32_e32 v9, v0
	v_mov_b32_e32 v10, v0
	v_mov_b32_e32 v11, v0
	v_mov_b32_e32 v16, v0
	v_mov_b32_e32 v17, v0
	v_mov_b32_e32 v18, v0
	v_mov_b32_e32 v19, v0
	v_mov_b32_e32 v24, v0
	v_mov_b32_e32 v25, v0
	v_mov_b32_e32 v26, v0
	v_mov_b32_e32 v27, v0
	v_mov_b32_e32 v32, v0
	v_mov_b32_e32 v33, v0
	v_mov_b32_e32 v34, v0
	v_mov_b32_e32 v35, v0
	v_mov_b32_e32 v40, v0
	v_mov_b32_e32 v41, v0
	v_mov_b32_e32 v42, v0
	v_mov_b32_e32 v43, v0
	v_mov_b32_e32 v48, v0
	v_mov_b32_e32 v49, v0
	v_mov_b32_e32 v50, v0
	v_mov_b32_e32 v51, v0
	v_mov_b32_e32 v56, v0
	v_mov_b32_e32 v57, v0
	v_mov_b32_e32 v58, v0
	v_mov_b32_e32 v59, v0
	v_mov_b32_e32 v4, v0
	v_mov_b32_e32 v5, v0
	v_mov_b32_e32 v6, v0
	v_mov_b32_e32 v7, v0
	v_mov_b32_e32 v12, v0
	v_mov_b32_e32 v13, v0
	v_mov_b32_e32 v14, v0
	v_mov_b32_e32 v15, v0
	v_mov_b32_e32 v20, v0
	v_mov_b32_e32 v21, v0
	v_mov_b32_e32 v22, v0
	v_mov_b32_e32 v23, v0
	v_mov_b32_e32 v28, v0
	v_mov_b32_e32 v29, v0
	v_mov_b32_e32 v30, v0
	v_mov_b32_e32 v31, v0
	v_mov_b32_e32 v36, v0
	v_mov_b32_e32 v37, v0
	v_mov_b32_e32 v38, v0
	v_mov_b32_e32 v39, v0
	v_mov_b32_e32 v44, v0
	v_mov_b32_e32 v45, v0
	v_mov_b32_e32 v46, v0
	v_mov_b32_e32 v47, v0
	v_mov_b32_e32 v52, v0
	v_mov_b32_e32 v53, v0
	v_mov_b32_e32 v54, v0
	v_mov_b32_e32 v55, v0
	v_mov_b32_e32 v60, v0
	v_mov_b32_e32 v61, v0
	v_mov_b32_e32 v62, v0
	v_mov_b32_e32 v63, v0
	v_mov_b32_e32 v64, v0
	v_mov_b32_e32 v65, v0
	v_mov_b32_e32 v66, v0
	v_mov_b32_e32 v67, v0
	v_mov_b32_e32 v72, v0
	v_mov_b32_e32 v73, v0
	v_mov_b32_e32 v74, v0
	v_mov_b32_e32 v75, v0
	v_mov_b32_e32 v80, v0
	v_mov_b32_e32 v81, v0
	v_mov_b32_e32 v82, v0
	v_mov_b32_e32 v83, v0
	v_mov_b32_e32 v88, v0
	v_mov_b32_e32 v89, v0
	v_mov_b32_e32 v90, v0
	v_mov_b32_e32 v91, v0
	v_mov_b32_e32 v96, v0
	v_mov_b32_e32 v97, v0
	v_mov_b32_e32 v98, v0
	v_mov_b32_e32 v99, v0
	v_mov_b32_e32 v104, v0
	v_mov_b32_e32 v105, v0
	v_mov_b32_e32 v106, v0
	v_mov_b32_e32 v107, v0
	v_mov_b32_e32 v112, v0
	v_mov_b32_e32 v113, v0
	v_mov_b32_e32 v114, v0
	v_mov_b32_e32 v115, v0
	v_mov_b32_e32 v120, v0
	v_mov_b32_e32 v121, v0
	v_mov_b32_e32 v122, v0
	v_mov_b32_e32 v123, v0
	v_mov_b32_e32 v68, v0
	v_mov_b32_e32 v69, v0
	v_mov_b32_e32 v70, v0
	v_mov_b32_e32 v71, v0
	v_mov_b32_e32 v76, v0
	v_mov_b32_e32 v77, v0
	v_mov_b32_e32 v78, v0
	v_mov_b32_e32 v79, v0
	v_mov_b32_e32 v84, v0
	v_mov_b32_e32 v85, v0
	v_mov_b32_e32 v86, v0
	v_mov_b32_e32 v87, v0
	v_mov_b32_e32 v92, v0
	v_mov_b32_e32 v93, v0
	v_mov_b32_e32 v94, v0
	v_mov_b32_e32 v95, v0
	v_mov_b32_e32 v100, v0
	v_mov_b32_e32 v101, v0
	v_mov_b32_e32 v102, v0
	v_mov_b32_e32 v103, v0
	v_mov_b32_e32 v108, v0
	v_mov_b32_e32 v109, v0
	v_mov_b32_e32 v110, v0
	v_mov_b32_e32 v111, v0
	v_mov_b32_e32 v116, v0
	v_mov_b32_e32 v117, v0
	v_mov_b32_e32 v118, v0
	v_mov_b32_e32 v119, v0
	v_mov_b32_e32 v124, v0
	v_mov_b32_e32 v125, v0
	v_mov_b32_e32 v126, v0
	v_mov_b32_e32 v127, v0
	.p2alignl 6, 3212836864

.LBB0_359:
	s_add_u32 s42, s8, 0x100
	v_mov_b32_e32 v0, 0
	s_addc_u32 s43, s9, 0
	s_mov_b32 s44, -2
	v_mov_b32_e32 v1, v0
	v_mov_b32_e32 v2, v0
	v_mov_b32_e32 v3, v0
	v_mov_b32_e32 v4, v0
	v_mov_b32_e32 v5, v0
	v_mov_b32_e32 v6, v0
	v_mov_b32_e32 v7, v0
	v_mov_b32_e32 v16, v0
	v_mov_b32_e32 v17, v0
	v_mov_b32_e32 v18, v0
	v_mov_b32_e32 v19, v0
	v_mov_b32_e32 v20, v0
	v_mov_b32_e32 v21, v0
	v_mov_b32_e32 v22, v0
	v_mov_b32_e32 v23, v0
	v_mov_b32_e32 v32, v0
	v_mov_b32_e32 v33, v0
	v_mov_b32_e32 v34, v0
	v_mov_b32_e32 v35, v0
	v_mov_b32_e32 v36, v0
	v_mov_b32_e32 v37, v0
	v_mov_b32_e32 v38, v0
	v_mov_b32_e32 v39, v0
	v_mov_b32_e32 v48, v0
	v_mov_b32_e32 v49, v0
	v_mov_b32_e32 v50, v0
	v_mov_b32_e32 v51, v0
	v_mov_b32_e32 v52, v0
	v_mov_b32_e32 v53, v0
	v_mov_b32_e32 v54, v0
	v_mov_b32_e32 v55, v0
	v_mov_b32_e32 v8, v0
	v_mov_b32_e32 v9, v0
	v_mov_b32_e32 v10, v0
	v_mov_b32_e32 v11, v0
	v_mov_b32_e32 v12, v0
	v_mov_b32_e32 v13, v0
	v_mov_b32_e32 v14, v0
	v_mov_b32_e32 v15, v0
	v_mov_b32_e32 v24, v0
	v_mov_b32_e32 v25, v0
	v_mov_b32_e32 v26, v0
	v_mov_b32_e32 v27, v0
	v_mov_b32_e32 v28, v0
	v_mov_b32_e32 v29, v0
	v_mov_b32_e32 v30, v0
	v_mov_b32_e32 v31, v0
	v_mov_b32_e32 v40, v0
	v_mov_b32_e32 v41, v0
	v_mov_b32_e32 v42, v0
	v_mov_b32_e32 v43, v0
	v_mov_b32_e32 v44, v0
	v_mov_b32_e32 v45, v0
	v_mov_b32_e32 v46, v0
	v_mov_b32_e32 v47, v0
	v_mov_b32_e32 v56, v0
	v_mov_b32_e32 v57, v0
	v_mov_b32_e32 v58, v0
	v_mov_b32_e32 v59, v0
	v_mov_b32_e32 v60, v0
	v_mov_b32_e32 v61, v0
	v_mov_b32_e32 v62, v0
	v_mov_b32_e32 v63, v0
	v_mov_b32_e32 v64, v0
	v_mov_b32_e32 v65, v0
	v_mov_b32_e32 v66, v0
	v_mov_b32_e32 v67, v0
	v_mov_b32_e32 v68, v0
	v_mov_b32_e32 v69, v0
	v_mov_b32_e32 v70, v0
	v_mov_b32_e32 v71, v0
	v_mov_b32_e32 v80, v0
	v_mov_b32_e32 v81, v0
	v_mov_b32_e32 v82, v0
	v_mov_b32_e32 v83, v0
	v_mov_b32_e32 v84, v0
	v_mov_b32_e32 v85, v0
	v_mov_b32_e32 v86, v0
	v_mov_b32_e32 v87, v0
	v_mov_b32_e32 v96, v0
	v_mov_b32_e32 v97, v0
	v_mov_b32_e32 v98, v0
	v_mov_b32_e32 v99, v0
	v_mov_b32_e32 v100, v0
	v_mov_b32_e32 v101, v0
	v_mov_b32_e32 v102, v0
	v_mov_b32_e32 v103, v0
	v_mov_b32_e32 v112, v0
	v_mov_b32_e32 v113, v0
	v_mov_b32_e32 v114, v0
	v_mov_b32_e32 v115, v0
	v_mov_b32_e32 v116, v0
	v_mov_b32_e32 v117, v0
	v_mov_b32_e32 v118, v0
	v_mov_b32_e32 v119, v0
	v_mov_b32_e32 v72, v0
	v_mov_b32_e32 v73, v0
	v_mov_b32_e32 v74, v0
	v_mov_b32_e32 v75, v0
	v_mov_b32_e32 v76, v0
	v_mov_b32_e32 v77, v0
	v_mov_b32_e32 v78, v0
	v_mov_b32_e32 v79, v0
	v_mov_b32_e32 v88, v0
	v_mov_b32_e32 v89, v0
	v_mov_b32_e32 v90, v0
	v_mov_b32_e32 v91, v0
	v_mov_b32_e32 v92, v0
	v_mov_b32_e32 v93, v0
	v_mov_b32_e32 v94, v0
	v_mov_b32_e32 v95, v0
	v_mov_b32_e32 v104, v0
	v_mov_b32_e32 v105, v0
	v_mov_b32_e32 v106, v0
	v_mov_b32_e32 v107, v0
	v_mov_b32_e32 v108, v0
	v_mov_b32_e32 v109, v0
	v_mov_b32_e32 v110, v0
	v_mov_b32_e32 v111, v0
	v_mov_b32_e32 v120, v0
	v_mov_b32_e32 v121, v0
	v_mov_b32_e32 v122, v0
	v_mov_b32_e32 v123, v0
	v_mov_b32_e32 v124, v0
	v_mov_b32_e32 v125, v0
	v_mov_b32_e32 v126, v0
	v_mov_b32_e32 v127, v0
	.p2alignl 6, 3212836864

.LBB0_587:
	s_ashr_i32 s37, s36, 31
	s_lshl_b64 s[14:15], s[36:37], 19
	s_add_u32 s38, s90, s14
	s_addc_u32 s39, s91, s15
	s_and_b64 s[14:15], s[6:7], exec
	s_cselect_b32 s9, s39, s11
	s_cselect_b32 s16, s38, s10
	s_ashr_i32 s35, s34, 31
	s_lshl_b64 s[14:15], s[34:35], 19
	s_add_u32 s40, s0, s14
	s_addc_u32 s41, s1, s15
	s_and_b64 s[14:15], s[6:7], exec
	s_cselect_b32 s17, s41, s13
	s_cselect_b32 s35, s40, s12
	s_add_u32 s10, s10, 0x40080
	s_addc_u32 s11, s11, 0
	s_add_u32 s37, s12, 0x100
	v_mov_b32_e32 v0, 0
	s_addc_u32 s42, s13, 0
	s_mov_b32 s43, -2
	v_mov_b32_e32 v1, v0
	v_mov_b32_e32 v2, v0
	s_waitcnt lgkmcnt(0)
	v_mov_b32_e32 v3, v0
	v_mov_b32_e32 v4, v0
	v_mov_b32_e32 v5, v0
	v_mov_b32_e32 v6, v0
	v_mov_b32_e32 v7, v0
	v_mov_b32_e32 v16, v0
	v_mov_b32_e32 v17, v0
	v_mov_b32_e32 v18, v0
	v_mov_b32_e32 v19, v0
	v_mov_b32_e32 v20, v0
	v_mov_b32_e32 v21, v0
	v_mov_b32_e32 v22, v0
	v_mov_b32_e32 v23, v0
	v_mov_b32_e32 v32, v0
	v_mov_b32_e32 v33, v0
	v_mov_b32_e32 v34, v0
	v_mov_b32_e32 v35, v0
	v_mov_b32_e32 v36, v0
	v_mov_b32_e32 v37, v0
	v_mov_b32_e32 v38, v0
	v_mov_b32_e32 v39, v0
	v_mov_b32_e32 v48, v0
	v_mov_b32_e32 v49, v0
	v_mov_b32_e32 v50, v0
	v_mov_b32_e32 v51, v0
	v_mov_b32_e32 v52, v0
	v_mov_b32_e32 v53, v0
	v_mov_b32_e32 v54, v0
	v_mov_b32_e32 v55, v0
	v_mov_b32_e32 v8, v0
	v_mov_b32_e32 v9, v0
	v_mov_b32_e32 v10, v0
	v_mov_b32_e32 v11, v0
	v_mov_b32_e32 v12, v0
	v_mov_b32_e32 v13, v0
	v_mov_b32_e32 v14, v0
	v_mov_b32_e32 v15, v0
	v_mov_b32_e32 v24, v0
	v_mov_b32_e32 v25, v0
	v_mov_b32_e32 v26, v0
	v_mov_b32_e32 v27, v0
	v_mov_b32_e32 v28, v0
	v_mov_b32_e32 v29, v0
	v_mov_b32_e32 v30, v0
	v_mov_b32_e32 v31, v0
	v_mov_b32_e32 v40, v0
	v_mov_b32_e32 v41, v0
	v_mov_b32_e32 v42, v0
	v_mov_b32_e32 v43, v0
	v_mov_b32_e32 v44, v0
	v_mov_b32_e32 v45, v0
	v_mov_b32_e32 v46, v0
	v_mov_b32_e32 v47, v0
	v_mov_b32_e32 v56, v0
	v_mov_b32_e32 v57, v0
	v_mov_b32_e32 v58, v0
	v_mov_b32_e32 v59, v0
	v_mov_b32_e32 v60, v0
	v_mov_b32_e32 v61, v0
	v_mov_b32_e32 v62, v0
	v_mov_b32_e32 v63, v0
	v_mov_b32_e32 v64, v0
	v_mov_b32_e32 v65, v0
	v_mov_b32_e32 v66, v0
	v_mov_b32_e32 v67, v0
	v_mov_b32_e32 v68, v0
	v_mov_b32_e32 v69, v0
	v_mov_b32_e32 v70, v0
	v_mov_b32_e32 v71, v0
	v_mov_b32_e32 v80, v0
	v_mov_b32_e32 v81, v0
	v_mov_b32_e32 v82, v0
	v_mov_b32_e32 v83, v0
	v_mov_b32_e32 v84, v0
	v_mov_b32_e32 v85, v0
	v_mov_b32_e32 v86, v0
	v_mov_b32_e32 v87, v0
	v_mov_b32_e32 v96, v0
	v_mov_b32_e32 v97, v0
	v_mov_b32_e32 v98, v0
	v_mov_b32_e32 v99, v0
	v_mov_b32_e32 v100, v0
	v_mov_b32_e32 v101, v0
	v_mov_b32_e32 v102, v0
	v_mov_b32_e32 v103, v0
	v_mov_b32_e32 v112, v0
	v_mov_b32_e32 v113, v0
	v_mov_b32_e32 v114, v0
	v_mov_b32_e32 v115, v0
	v_mov_b32_e32 v116, v0
	v_mov_b32_e32 v117, v0
	v_mov_b32_e32 v118, v0
	v_mov_b32_e32 v119, v0
	v_mov_b32_e32 v72, v0
	v_mov_b32_e32 v73, v0
	v_mov_b32_e32 v74, v0
	v_mov_b32_e32 v75, v0
	v_mov_b32_e32 v76, v0
	v_mov_b32_e32 v77, v0
	v_mov_b32_e32 v78, v0
	v_mov_b32_e32 v79, v0
	v_mov_b32_e32 v88, v0
	v_mov_b32_e32 v89, v0
	v_mov_b32_e32 v90, v0
	v_mov_b32_e32 v91, v0
	v_mov_b32_e32 v92, v0
	v_mov_b32_e32 v93, v0
	v_mov_b32_e32 v94, v0
	v_mov_b32_e32 v95, v0
	v_mov_b32_e32 v104, v0
	v_mov_b32_e32 v105, v0
	v_mov_b32_e32 v106, v0
	v_mov_b32_e32 v107, v0
	v_mov_b32_e32 v108, v0
	v_mov_b32_e32 v109, v0
	v_mov_b32_e32 v110, v0
	v_mov_b32_e32 v111, v0
	v_mov_b32_e32 v120, v0
	v_mov_b32_e32 v121, v0
	v_mov_b32_e32 v122, v0
	v_mov_b32_e32 v123, v0
	v_mov_b32_e32 v124, v0
	v_mov_b32_e32 v125, v0
	v_mov_b32_e32 v126, v0
	v_mov_b32_e32 v127, v0
	.p2alignl 6, 3212836864

.LBB0_763:
	s_ashr_i32 s21, s20, 31
	s_lshl_b64 s[22:23], s[20:21], 19
	s_add_u32 s22, s10, s22
	s_addc_u32 s23, s11, s23
	s_and_b64 s[24:25], s[8:9], exec
	s_cselect_b32 s21, s23, s27
	s_cselect_b32 s48, s22, s26
	s_ashr_i32 s19, s18, 31
	s_lshl_b64 s[24:25], s[18:19], 19
	s_add_u32 s24, s90, s24
	s_addc_u32 s25, s91, s25
	s_and_b64 s[34:35], s[8:9], exec
	s_mov_b32 s57, s49
	s_cselect_b32 s19, s25, s31
	s_cselect_b32 s49, s24, s30
	s_add_u32 s26, s26, 0x40080
	s_addc_u32 s27, s27, 0
	s_add_u32 s50, s30, 0x100
	v_mov_b32_e32 v0, 0
	s_addc_u32 s51, s31, 0
	s_mov_b32 s52, -2
	v_mov_b32_e32 v1, v0
	v_mov_b32_e32 v2, v0
	v_mov_b32_e32 v3, v0
	v_mov_b32_e32 v32, v0
	v_mov_b32_e32 v33, v0
	v_mov_b32_e32 v34, v0
	v_mov_b32_e32 v35, v0
	v_mov_b32_e32 v4, v0
	v_mov_b32_e32 v5, v0
	v_mov_b32_e32 v6, v0
	v_mov_b32_e32 v7, v0
	v_mov_b32_e32 v36, v0
	v_mov_b32_e32 v37, v0
	v_mov_b32_e32 v38, v0
	v_mov_b32_e32 v39, v0
	v_mov_b32_e32 v8, v0
	v_mov_b32_e32 v9, v0
	v_mov_b32_e32 v10, v0
	v_mov_b32_e32 v11, v0
	v_mov_b32_e32 v40, v0
	v_mov_b32_e32 v41, v0
	v_mov_b32_e32 v42, v0
	v_mov_b32_e32 v43, v0
	v_mov_b32_e32 v12, v0
	v_mov_b32_e32 v13, v0
	v_mov_b32_e32 v14, v0
	v_mov_b32_e32 v15, v0
	v_mov_b32_e32 v44, v0
	v_mov_b32_e32 v45, v0
	v_mov_b32_e32 v46, v0
	v_mov_b32_e32 v47, v0
	v_mov_b32_e32 v64, v0
	v_mov_b32_e32 v65, v0
	v_mov_b32_e32 v66, v0
	v_mov_b32_e32 v67, v0
	v_mov_b32_e32 v96, v0
	v_mov_b32_e32 v97, v0
	v_mov_b32_e32 v98, v0
	v_mov_b32_e32 v99, v0
	v_mov_b32_e32 v68, v0
	v_mov_b32_e32 v69, v0
	v_mov_b32_e32 v70, v0
	v_mov_b32_e32 v71, v0
	v_mov_b32_e32 v100, v0
	v_mov_b32_e32 v101, v0
	v_mov_b32_e32 v102, v0
	v_mov_b32_e32 v103, v0
	v_mov_b32_e32 v72, v0
	v_mov_b32_e32 v73, v0
	v_mov_b32_e32 v74, v0
	v_mov_b32_e32 v75, v0
	v_mov_b32_e32 v104, v0
	v_mov_b32_e32 v105, v0
	v_mov_b32_e32 v106, v0
	v_mov_b32_e32 v107, v0
	v_mov_b32_e32 v76, v0
	v_mov_b32_e32 v77, v0
	v_mov_b32_e32 v78, v0
	v_mov_b32_e32 v79, v0
	v_mov_b32_e32 v108, v0
	v_mov_b32_e32 v109, v0
	v_mov_b32_e32 v110, v0
	v_mov_b32_e32 v111, v0
	v_mov_b32_e32 v16, v0
	v_mov_b32_e32 v17, v0
	v_mov_b32_e32 v18, v0
	v_mov_b32_e32 v19, v0
	v_mov_b32_e32 v48, v0
	v_mov_b32_e32 v49, v0
	v_mov_b32_e32 v50, v0
	v_mov_b32_e32 v51, v0
	v_mov_b32_e32 v20, v0
	v_mov_b32_e32 v21, v0
	v_mov_b32_e32 v22, v0
	v_mov_b32_e32 v23, v0
	v_mov_b32_e32 v52, v0
	v_mov_b32_e32 v53, v0
	v_mov_b32_e32 v54, v0
	v_mov_b32_e32 v55, v0
	v_mov_b32_e32 v24, v0
	v_mov_b32_e32 v25, v0
	v_mov_b32_e32 v26, v0
	v_mov_b32_e32 v27, v0
	v_mov_b32_e32 v56, v0
	v_mov_b32_e32 v57, v0
	v_mov_b32_e32 v58, v0
	v_mov_b32_e32 v59, v0
	v_mov_b32_e32 v28, v0
	v_mov_b32_e32 v29, v0
	v_mov_b32_e32 v30, v0
	v_mov_b32_e32 v31, v0
	v_mov_b32_e32 v60, v0
	v_mov_b32_e32 v61, v0
	v_mov_b32_e32 v62, v0
	v_mov_b32_e32 v63, v0
	v_mov_b32_e32 v80, v0
	v_mov_b32_e32 v81, v0
	v_mov_b32_e32 v82, v0
	v_mov_b32_e32 v83, v0
	v_mov_b32_e32 v112, v0
	v_mov_b32_e32 v113, v0
	v_mov_b32_e32 v114, v0
	v_mov_b32_e32 v115, v0
	v_mov_b32_e32 v84, v0
	v_mov_b32_e32 v85, v0
	v_mov_b32_e32 v86, v0
	v_mov_b32_e32 v87, v0
	v_mov_b32_e32 v116, v0
	v_mov_b32_e32 v117, v0
	v_mov_b32_e32 v118, v0
	v_mov_b32_e32 v119, v0
	v_mov_b32_e32 v88, v0
	v_mov_b32_e32 v89, v0
	v_mov_b32_e32 v90, v0
	v_mov_b32_e32 v91, v0
	v_mov_b32_e32 v120, v0
	v_mov_b32_e32 v121, v0
	v_mov_b32_e32 v122, v0
	v_mov_b32_e32 v123, v0
	v_mov_b32_e32 v92, v0
	v_mov_b32_e32 v93, v0
	v_mov_b32_e32 v94, v0
	v_mov_b32_e32 v95, v0
	v_mov_b32_e32 v124, v0
	v_mov_b32_e32 v125, v0
	v_mov_b32_e32 v126, v0
	v_mov_b32_e32 v127, v0
	.p2alignl 6, 3212836864

.Lmla_early_skip1:
	v_add_u32_e32 v173, s67, v173
	v_add_u32_e32 v197, s67, v197
	v_add_u32_e32 v193, s67, v193
	v_add_u32_e32 v195, s67, v195
	v_add_u32_e32 v192, s67, v192
	v_add_u32_e32 v198, s67, v198
	v_add_u32_e32 v194, s67, v194
	v_add_u32_e32 v196, s67, v196
	s_sub_i32 s67, 0, s67
	s_xor_b32 s66, s66, 0x8000
	s_mov_b64 s[14:15], 0xc000
	v_lshl_add_u64 v[180:181], v[180:181], 0, s[14:15]
	v_lshl_add_u64 v[182:183], v[182:183], 0, s[14:15]
	s_add_i32 s13, s13, 4
	s_add_i32 s12, s12, 4
	s_mov_b64 s[14:15], 0x200
	s_cmp_gt_u32 s13, 55
	v_lshl_add_u64 v[184:185], v[184:185], 0, s[14:15]
	s_cbranch_scc1 .LBB0_1209
	.p2alignl 6, 3212836864

.LBB0_1334:
	s_ashr_i32 s17, s16, 31
	s_lshl_b64 s[18:19], s[16:17], 18
	s_add_u32 s18, s33, s18
	s_addc_u32 s19, s34, s19
	s_and_b64 s[20:21], s[6:7], exec
	s_cselect_b32 s17, s19, s9
	s_cselect_b32 s49, s18, s8
	s_ashr_i32 s15, s14, 31
	s_lshl_b64 s[20:21], s[14:15], 18
	s_add_u32 s20, s35, s20
	s_addc_u32 s21, s36, s21
	s_and_b64 s[24:25], s[6:7], exec
	s_cselect_b32 s15, s21, s23
	s_cselect_b32 s50, s20, s22
	s_add_u32 s8, s8, 0x20080
	s_addc_u32 s9, s9, 0
	s_add_u32 s51, s22, 0x100
	v_mov_b32_e32 v0, 0
	s_addc_u32 s52, s23, 0
	s_mov_b32 s53, -2
	v_mov_b32_e32 v1, v0
	v_mov_b32_e32 v2, v0
	v_mov_b32_e32 v3, v0
	v_mov_b32_e32 v4, v0
	v_mov_b32_e32 v5, v0
	v_mov_b32_e32 v6, v0
	v_mov_b32_e32 v7, v0
	v_mov_b32_e32 v16, v0
	v_mov_b32_e32 v17, v0
	v_mov_b32_e32 v18, v0
	v_mov_b32_e32 v19, v0
	v_mov_b32_e32 v20, v0
	v_mov_b32_e32 v21, v0
	v_mov_b32_e32 v22, v0
	v_mov_b32_e32 v23, v0
	v_mov_b32_e32 v32, v0
	v_mov_b32_e32 v33, v0
	v_mov_b32_e32 v34, v0
	v_mov_b32_e32 v35, v0
	v_mov_b32_e32 v36, v0
	v_mov_b32_e32 v37, v0
	v_mov_b32_e32 v38, v0
	v_mov_b32_e32 v39, v0
	v_mov_b32_e32 v48, v0
	v_mov_b32_e32 v49, v0
	v_mov_b32_e32 v50, v0
	v_mov_b32_e32 v51, v0
	v_mov_b32_e32 v52, v0
	v_mov_b32_e32 v53, v0
	v_mov_b32_e32 v54, v0
	v_mov_b32_e32 v55, v0
	v_mov_b32_e32 v8, v0
	v_mov_b32_e32 v9, v0
	v_mov_b32_e32 v10, v0
	v_mov_b32_e32 v11, v0
	v_mov_b32_e32 v12, v0
	v_mov_b32_e32 v13, v0
	v_mov_b32_e32 v14, v0
	v_mov_b32_e32 v15, v0
	v_mov_b32_e32 v24, v0
	v_mov_b32_e32 v25, v0
	v_mov_b32_e32 v26, v0
	v_mov_b32_e32 v27, v0
	v_mov_b32_e32 v28, v0
	v_mov_b32_e32 v29, v0
	v_mov_b32_e32 v30, v0
	v_mov_b32_e32 v31, v0
	v_mov_b32_e32 v40, v0
	v_mov_b32_e32 v41, v0
	v_mov_b32_e32 v42, v0
	v_mov_b32_e32 v43, v0
	v_mov_b32_e32 v44, v0
	v_mov_b32_e32 v45, v0
	v_mov_b32_e32 v46, v0
	v_mov_b32_e32 v47, v0
	v_mov_b32_e32 v56, v0
	v_mov_b32_e32 v57, v0
	v_mov_b32_e32 v58, v0
	v_mov_b32_e32 v59, v0
	v_mov_b32_e32 v60, v0
	v_mov_b32_e32 v61, v0
	v_mov_b32_e32 v62, v0
	v_mov_b32_e32 v63, v0
	v_mov_b32_e32 v64, v0
	v_mov_b32_e32 v65, v0
	v_mov_b32_e32 v66, v0
	v_mov_b32_e32 v67, v0
	v_mov_b32_e32 v68, v0
	v_mov_b32_e32 v69, v0
	v_mov_b32_e32 v70, v0
	v_mov_b32_e32 v71, v0
	v_mov_b32_e32 v80, v0
	v_mov_b32_e32 v81, v0
	v_mov_b32_e32 v82, v0
	v_mov_b32_e32 v83, v0
	v_mov_b32_e32 v84, v0
	v_mov_b32_e32 v85, v0
	v_mov_b32_e32 v86, v0
	v_mov_b32_e32 v87, v0
	v_mov_b32_e32 v96, v0
	v_mov_b32_e32 v97, v0
	v_mov_b32_e32 v98, v0
	v_mov_b32_e32 v99, v0
	v_mov_b32_e32 v100, v0
	v_mov_b32_e32 v101, v0
	v_mov_b32_e32 v102, v0
	v_mov_b32_e32 v103, v0
	v_mov_b32_e32 v112, v0
	v_mov_b32_e32 v113, v0
	v_mov_b32_e32 v114, v0
	v_mov_b32_e32 v115, v0
	v_mov_b32_e32 v116, v0
	v_mov_b32_e32 v117, v0
	v_mov_b32_e32 v118, v0
	v_mov_b32_e32 v119, v0
	v_mov_b32_e32 v72, v0
	v_mov_b32_e32 v73, v0
	v_mov_b32_e32 v74, v0
	v_mov_b32_e32 v75, v0
	v_mov_b32_e32 v76, v0
	v_mov_b32_e32 v77, v0
	v_mov_b32_e32 v78, v0
	v_mov_b32_e32 v79, v0
	v_mov_b32_e32 v88, v0
	v_mov_b32_e32 v89, v0
	v_mov_b32_e32 v90, v0
	v_mov_b32_e32 v91, v0
	v_mov_b32_e32 v92, v0
	v_mov_b32_e32 v93, v0
	v_mov_b32_e32 v94, v0
	v_mov_b32_e32 v95, v0
	v_mov_b32_e32 v104, v0
	v_mov_b32_e32 v105, v0
	v_mov_b32_e32 v106, v0
	v_mov_b32_e32 v107, v0
	v_mov_b32_e32 v108, v0
	v_mov_b32_e32 v109, v0
	v_mov_b32_e32 v110, v0
	v_mov_b32_e32 v111, v0
	v_mov_b32_e32 v120, v0
	v_mov_b32_e32 v121, v0
	v_mov_b32_e32 v122, v0
	v_mov_b32_e32 v123, v0
	v_mov_b32_e32 v124, v0
	v_mov_b32_e32 v125, v0
	v_mov_b32_e32 v126, v0
	v_mov_b32_e32 v127, v0
	.p2alignl 6, 3212836864

.LBB0_1437:
	s_ashr_i32 s13, s12, 31
	s_lshl_b64 s[14:15], s[12:13], 19
	s_add_u32 s14, s24, s14
	s_addc_u32 s15, s25, s15
	s_and_b64 s[16:17], s[4:5], exec
	s_cselect_b32 s13, s15, s19
	s_cselect_b32 s44, s14, s18
	s_ashr_i32 s11, s10, 31
	s_lshl_b64 s[16:17], s[10:11], 19
	s_add_u32 s16, s26, s16
	s_addc_u32 s17, s27, s17
	s_and_b64 s[22:23], s[4:5], exec
	s_cselect_b32 s11, s17, s21
	s_cselect_b32 s45, s16, s20
	s_add_u32 s18, s18, 0x40080
	s_addc_u32 s19, s19, 0
	s_add_u32 s46, s20, 0x100
	v_mov_b32_e32 v0, 0
	s_mov_b32 s53, s49
	s_addc_u32 s47, s21, 0
	s_mov_b32 s48, -2
	v_mov_b32_e32 v1, v0
	v_mov_b32_e32 v2, v0
	v_mov_b32_e32 v3, v0
	v_mov_b32_e32 v4, v0
	v_mov_b32_e32 v5, v0
	v_mov_b32_e32 v6, v0
	v_mov_b32_e32 v7, v0
	v_mov_b32_e32 v16, v0
	v_mov_b32_e32 v17, v0
	v_mov_b32_e32 v18, v0
	v_mov_b32_e32 v19, v0
	v_mov_b32_e32 v20, v0
	v_mov_b32_e32 v21, v0
	v_mov_b32_e32 v22, v0
	v_mov_b32_e32 v23, v0
	v_mov_b32_e32 v32, v0
	v_mov_b32_e32 v33, v0
	v_mov_b32_e32 v34, v0
	v_mov_b32_e32 v35, v0
	v_mov_b32_e32 v36, v0
	v_mov_b32_e32 v37, v0
	v_mov_b32_e32 v38, v0
	v_mov_b32_e32 v39, v0
	v_mov_b32_e32 v48, v0
	v_mov_b32_e32 v49, v0
	v_mov_b32_e32 v50, v0
	v_mov_b32_e32 v51, v0
	v_mov_b32_e32 v52, v0
	v_mov_b32_e32 v53, v0
	v_mov_b32_e32 v54, v0
	v_mov_b32_e32 v55, v0
	v_mov_b32_e32 v8, v0
	v_mov_b32_e32 v9, v0
	v_mov_b32_e32 v10, v0
	v_mov_b32_e32 v11, v0
	v_mov_b32_e32 v12, v0
	v_mov_b32_e32 v13, v0
	v_mov_b32_e32 v14, v0
	v_mov_b32_e32 v15, v0
	v_mov_b32_e32 v24, v0
	v_mov_b32_e32 v25, v0
	v_mov_b32_e32 v26, v0
	v_mov_b32_e32 v27, v0
	v_mov_b32_e32 v28, v0
	v_mov_b32_e32 v29, v0
	v_mov_b32_e32 v30, v0
	v_mov_b32_e32 v31, v0
	v_mov_b32_e32 v40, v0
	v_mov_b32_e32 v41, v0
	v_mov_b32_e32 v42, v0
	v_mov_b32_e32 v43, v0
	v_mov_b32_e32 v44, v0
	v_mov_b32_e32 v45, v0
	v_mov_b32_e32 v46, v0
	v_mov_b32_e32 v47, v0
	v_mov_b32_e32 v56, v0
	v_mov_b32_e32 v57, v0
	v_mov_b32_e32 v58, v0
	v_mov_b32_e32 v59, v0
	v_mov_b32_e32 v60, v0
	v_mov_b32_e32 v61, v0
	v_mov_b32_e32 v62, v0
	v_mov_b32_e32 v63, v0
	v_mov_b32_e32 v64, v0
	v_mov_b32_e32 v65, v0
	v_mov_b32_e32 v66, v0
	v_mov_b32_e32 v67, v0
	v_mov_b32_e32 v68, v0
	v_mov_b32_e32 v69, v0
	v_mov_b32_e32 v70, v0
	v_mov_b32_e32 v71, v0
	v_mov_b32_e32 v80, v0
	v_mov_b32_e32 v81, v0
	v_mov_b32_e32 v82, v0
	v_mov_b32_e32 v83, v0
	v_mov_b32_e32 v84, v0
	v_mov_b32_e32 v85, v0
	v_mov_b32_e32 v86, v0
	v_mov_b32_e32 v87, v0
	v_mov_b32_e32 v96, v0
	v_mov_b32_e32 v97, v0
	v_mov_b32_e32 v98, v0
	v_mov_b32_e32 v99, v0
	v_mov_b32_e32 v100, v0
	v_mov_b32_e32 v101, v0
	v_mov_b32_e32 v102, v0
	v_mov_b32_e32 v103, v0
	v_mov_b32_e32 v112, v0
	v_mov_b32_e32 v113, v0
	v_mov_b32_e32 v114, v0
	v_mov_b32_e32 v115, v0
	v_mov_b32_e32 v116, v0
	v_mov_b32_e32 v117, v0
	v_mov_b32_e32 v118, v0
	v_mov_b32_e32 v119, v0
	v_mov_b32_e32 v72, v0
	v_mov_b32_e32 v73, v0
	v_mov_b32_e32 v74, v0
	v_mov_b32_e32 v75, v0
	v_mov_b32_e32 v76, v0
	v_mov_b32_e32 v77, v0
	v_mov_b32_e32 v78, v0
	v_mov_b32_e32 v79, v0
	v_mov_b32_e32 v88, v0
	v_mov_b32_e32 v89, v0
	v_mov_b32_e32 v90, v0
	v_mov_b32_e32 v91, v0
	v_mov_b32_e32 v92, v0
	v_mov_b32_e32 v93, v0
	v_mov_b32_e32 v94, v0
	v_mov_b32_e32 v95, v0
	v_mov_b32_e32 v104, v0
	v_mov_b32_e32 v105, v0
	v_mov_b32_e32 v106, v0
	v_mov_b32_e32 v107, v0
	v_mov_b32_e32 v108, v0
	v_mov_b32_e32 v109, v0
	v_mov_b32_e32 v110, v0
	v_mov_b32_e32 v111, v0
	v_mov_b32_e32 v120, v0
	v_mov_b32_e32 v121, v0
	v_mov_b32_e32 v122, v0
	v_mov_b32_e32 v123, v0
	v_mov_b32_e32 v124, v0
	v_mov_b32_e32 v125, v0
	v_mov_b32_e32 v126, v0
	v_mov_b32_e32 v127, v0
	.p2alignl 6, 3212836864
